# speedup vs baseline: 1.0202x; 1.0179x over previous
.LBB0_572:
	s_add_i32 s10, s12, 4
	s_cmp_ge_u32 s10, s19
	s_cbranch_scc1 .Lda_nodma
	s_and_b32 s10, s10, 3
	s_mulk_i32 s10, 0x5000
	s_add_i32 s10, s14, s10
	s_mov_b32 m0, s10
	s_nop 0
	global_load_lds_dwordx4 v[180:181], off
	s_add_i32 m0, s10, 0x3000
	s_nop 0
	global_load_lds_dwordx4 v[178:179], off

.LBB0_576:
	s_add_i32 s7, s12, 1
	s_and_b32 s10, s7, 3
	s_mulk_i32 s10, 0x5000
	v_add_u32_e32 v144, s10, v251
	v_add_u32_e32 v224, v144, v165
	v_add_u32_e32 v177, v144, v247
	ds_read_b128 v[132:135], v224
	ds_read_b128 v[136:139], v224 offset:4096
	ds_read_b128 v[140:143], v177
	ds_read_b128 v[128:131], v177 offset:4096
	v_exp_f32_e32 v194, v80
	v_exp_f32_e32 v182, v64
	v_exp_f32_e32 v195, v82
	v_exp_f32_e32 v183, v66
	v_exp_f32_e32 v200, v81
	v_exp_f32_e32 v184, v65
	v_exp_f32_e32 v201, v83
	v_exp_f32_e32 v185, v67
	v_exp_f32_e32 v206, v84
	v_exp_f32_e32 v186, v68
	v_exp_f32_e32 v207, v86
	v_exp_f32_e32 v187, v70
	v_exp_f32_e32 v210, v85
	v_exp_f32_e32 v188, v69
	v_exp_f32_e32 v211, v87
	v_exp_f32_e32 v189, v71
	v_exp_f32_e32 v196, v88
	v_exp_f32_e32 v190, v72
	v_exp_f32_e32 v197, v90
	v_exp_f32_e32 v191, v74
	v_exp_f32_e32 v202, v89
	v_exp_f32_e32 v192, v73
	v_exp_f32_e32 v203, v91
	v_exp_f32_e32 v193, v75
	v_exp_f32_e32 v208, v92
	v_exp_f32_e32 v198, v76
	v_exp_f32_e32 v209, v94
	v_exp_f32_e32 v199, v78
	v_exp_f32_e32 v212, v93
	v_exp_f32_e32 v204, v77
	v_exp_f32_e32 v213, v95
	v_exp_f32_e32 v205, v79
	v_pk_add_f32 v[64:65], v[194:195], v[182:183]
	v_pk_add_f32 v[66:67], v[200:201], v[184:185]
	v_pk_add_f32 v[68:69], v[206:207], v[186:187]
	v_pk_add_f32 v[70:71], v[210:211], v[188:189]
	v_pk_add_f32 v[64:65], v[68:69], v[64:65]
	v_pk_add_f32 v[66:67], v[70:71], v[66:67]
	v_pk_add_f32 v[68:69], v[196:197], v[190:191]
	v_pk_add_f32 v[70:71], v[202:203], v[192:193]
	v_pk_add_f32 v[64:65], v[68:69], v[64:65]
	v_pk_add_f32 v[66:67], v[70:71], v[66:67]
	v_pk_add_f32 v[68:69], v[208:209], v[198:199]
	v_pk_add_f32 v[70:71], v[212:213], v[204:205]
	v_pk_add_f32 v[64:65], v[68:69], v[64:65]
	v_pk_add_f32 v[66:67], v[70:71], v[66:67]
	s_nop 0
	v_pk_add_f32 v[64:65], v[64:65], v[66:67]
	s_nop 0
	v_add_f32_e32 v214, v64, v65
	v_cmp_ngt_f32_e32 vcc, s92, v214
	s_cbranch_vccnz .Lda_slow0

.LBB0_582:
	v_exp_f32_e32 v222, v80
	v_exp_f32_e32 v228, v64
	v_exp_f32_e32 v223, v82
	v_exp_f32_e32 v229, v66
	v_exp_f32_e32 v216, v81
	v_exp_f32_e32 v80, v65
	v_exp_f32_e32 v217, v83
	v_exp_f32_e32 v81, v67
	v_exp_f32_e32 v64, v84
	v_exp_f32_e32 v230, v68
	v_exp_f32_e32 v65, v86
	v_exp_f32_e32 v231, v70
	v_exp_f32_e32 v218, v85
	v_exp_f32_e32 v82, v69
	v_exp_f32_e32 v219, v87
	v_exp_f32_e32 v83, v71
	v_exp_f32_e32 v68, v88
	v_exp_f32_e32 v232, v72
	v_exp_f32_e32 v69, v90
	v_exp_f32_e32 v233, v74
	v_exp_f32_e32 v86, v89
	v_exp_f32_e32 v84, v73
	v_exp_f32_e32 v87, v91
	v_exp_f32_e32 v85, v75
	v_exp_f32_e32 v70, v92
	v_exp_f32_e32 v234, v76
	v_exp_f32_e32 v71, v94
	v_exp_f32_e32 v235, v78
	v_exp_f32_e32 v90, v93
	v_exp_f32_e32 v220, v77
	v_exp_f32_e32 v91, v95
	v_exp_f32_e32 v221, v79
	v_pk_add_f32 v[66:67], v[222:223], v[228:229]
	v_pk_add_f32 v[72:73], v[216:217], v[80:81]
	v_pk_add_f32 v[74:75], v[64:65], v[230:231]
	v_pk_add_f32 v[76:77], v[218:219], v[82:83]
	v_pk_add_f32 v[66:67], v[74:75], v[66:67]
	v_pk_add_f32 v[72:73], v[76:77], v[72:73]
	v_pk_add_f32 v[74:75], v[68:69], v[232:233]
	v_pk_add_f32 v[76:77], v[86:87], v[84:85]
	v_pk_add_f32 v[66:67], v[74:75], v[66:67]
	v_pk_add_f32 v[72:73], v[76:77], v[72:73]
	v_pk_add_f32 v[74:75], v[70:71], v[234:235]
	v_pk_add_f32 v[76:77], v[90:91], v[220:221]
	v_pk_add_f32 v[66:67], v[74:75], v[66:67]
	v_pk_add_f32 v[72:73], v[76:77], v[72:73]
	s_nop 0
	v_pk_add_f32 v[66:67], v[66:67], v[72:73]
	s_nop 0
	v_add_f32_e32 v226, v66, v67
	v_cmp_ngt_f32_e32 vcc, s92, v226
	s_cbranch_vccnz .Lda_slow1
.LBB0_584:
.LBB0_585:
	s_add_i32 s12, s12, 4
	s_cmp_ge_u32 s12, s19
	s_cselect_b64 s[10:11], -1, 0
.LBB0_587:
	v_cvt_pk_bf16_f32 v216, v222, v216
	v_cvt_pk_bf16_f32 v218, v64, v218
	v_cvt_pk_bf16_f32 v217, v223, v217
	v_cvt_pk_bf16_f32 v219, v65, v219
	v_cvt_pk_bf16_f32 v64, v228, v80
	v_cvt_pk_bf16_f32 v65, v229, v81
	v_cvt_pk_bf16_f32 v66, v230, v82
	v_cvt_pk_bf16_f32 v67, v231, v83
	v_cvt_pk_bf16_f32 v228, v194, v200
	v_cvt_pk_bf16_f32 v229, v195, v201
	v_cvt_pk_bf16_f32 v230, v206, v210
	v_cvt_pk_bf16_f32 v231, v207, v211
	s_waitcnt lgkmcnt(0)
	v_cvt_pk_bf16_f32 v92, v68, v86
	v_mfma_f32_32x32x16_bf16 v[32:47], v[156:159], v[228:231], v[32:47]
	v_cvt_pk_bf16_f32 v93, v69, v87
	v_cvt_pk_bf16_f32 v94, v70, v90
	v_cvt_pk_bf16_f32 v95, v71, v91
	v_cvt_pk_bf16_f32 v86, v182, v184
	v_cvt_pk_bf16_f32 v87, v183, v185
	v_cvt_pk_bf16_f32 v88, v186, v188
	v_cvt_pk_bf16_f32 v89, v187, v189
	v_mfma_f32_32x32x16_bf16 v[48:63], v[156:159], v[216:219], v[48:63]
	v_cvt_pk_bf16_f32 v68, v232, v84
	v_cvt_pk_bf16_f32 v69, v233, v85
	v_cvt_pk_bf16_f32 v70, v234, v220
	v_mfma_f32_32x32x16_bf16 v[0:15], v[152:155], v[228:231], v[0:15]
	v_cvt_pk_bf16_f32 v71, v235, v221
	s_and_b64 vcc, exec, s[10:11]
	v_mfma_f32_32x32x16_bf16 v[16:31], v[152:155], v[216:219], v[16:31]
	v_cvt_pk_bf16_f32 v152, v196, v202
	v_cvt_pk_bf16_f32 v153, v197, v203
	v_cvt_pk_bf16_f32 v154, v208, v212
	v_cvt_pk_bf16_f32 v155, v209, v213
	s_nop 1
	v_mfma_f32_32x32x16_bf16 v[32:47], v[148:151], v[152:155], v[32:47]
	v_mfma_f32_32x32x16_bf16 v[48:63], v[148:151], v[92:95], v[48:63]
	v_mfma_f32_32x32x16_bf16 v[0:15], v[144:147], v[152:155], v[0:15]
	v_mfma_f32_32x32x16_bf16 v[16:31], v[144:147], v[92:95], v[16:31]
	v_mfma_f32_32x32x16_bf16 v[32:47], v[140:143], v[86:89], v[32:47]
	v_mfma_f32_32x32x16_bf16 v[48:63], v[140:143], v[64:67], v[48:63]
	v_mfma_f32_32x32x16_bf16 v[0:15], v[136:139], v[86:89], v[0:15]
	v_mfma_f32_32x32x16_bf16 v[16:31], v[136:139], v[64:67], v[16:31]
	v_cvt_pk_bf16_f32 v64, v190, v192
	v_cvt_pk_bf16_f32 v65, v191, v193
	v_cvt_pk_bf16_f32 v66, v198, v204
	v_cvt_pk_bf16_f32 v67, v199, v205
	s_nop 1
	v_mfma_f32_32x32x16_bf16 v[32:47], v[132:135], v[64:67], v[32:47]
	v_mfma_f32_32x32x16_bf16 v[48:63], v[132:135], v[68:71], v[48:63]
	v_mfma_f32_32x32x16_bf16 v[0:15], v[128:131], v[64:67], v[0:15]
	v_mfma_f32_32x32x16_bf16 v[16:31], v[128:131], v[68:71], v[16:31]
	s_cbranch_vccnz .Lda_lastwait
	s_waitcnt vmcnt(2)

.Lda_slow1:
	ds_read_b128 v[64:67], v224
	ds_read_b128 v[216:219], v177
	ds_read_b128 v[80:83], v224 offset:4096
	s_mov_b64 s[2:3], -1
	s_waitcnt lgkmcnt(0)
	v_mfma_f32_32x32x16_bf16 v[64:79], v[64:67], v[104:107], 0
	v_mfma_f32_32x32x16_bf16 v[64:79], v[216:219], v[108:111], v[64:79]
	ds_read_b128 v[216:219], v177 offset:4096
	v_mfma_f32_32x32x16_bf16 v[80:95], v[80:83], v[104:107], 0
	s_nop 9
	v_sub_f32_e32 v64, v64, v176
	v_sub_f32_e32 v65, v65, v176
	v_sub_f32_e32 v215, v67, v176
	v_sub_f32_e32 v220, v72, v176
	v_sub_f32_e32 v222, v73, v176
	v_sub_f32_e32 v224, v74, v176
	v_sub_f32_e32 v225, v75, v176
	s_waitcnt lgkmcnt(0)
	v_mfma_f32_32x32x16_bf16 v[80:95], v[216:219], v[108:111], v[80:95]
	v_sub_f32_e32 v216, v69, v176
	v_sub_f32_e32 v218, v70, v176
	v_sub_f32_e32 v219, v71, v176
	v_sub_f32_e32 v228, v76, v176
	v_sub_f32_e32 v230, v77, v176
	v_sub_f32_e32 v232, v78, v176
	v_sub_f32_e32 v234, v79, v176
	s_nop 4
	v_sub_f32_e32 v80, v80, v176
	v_sub_f32_e32 v81, v81, v176
	v_max_f32_e32 v175, v64, v80
	v_max_f32_e32 v177, v65, v81
	v_max3_f32 v175, v175, s93, v177
	v_sub_f32_e32 v177, v66, v176
	v_sub_f32_e32 v82, v82, v176
	v_sub_f32_e32 v83, v83, v176
	v_max_f32_e32 v66, v177, v82
	v_max_f32_e32 v67, v215, v83
	v_max3_f32 v66, v175, v66, v67
	v_sub_f32_e32 v175, v68, v176
	v_sub_f32_e32 v84, v84, v176
	v_sub_f32_e32 v85, v85, v176
	v_max_f32_e32 v67, v175, v84
	v_max_f32_e32 v68, v216, v85
	v_sub_f32_e32 v86, v86, v176
	v_sub_f32_e32 v87, v87, v176
	v_max3_f32 v66, v66, v67, v68
	v_max_f32_e32 v67, v218, v86
	v_max_f32_e32 v68, v219, v87
	v_sub_f32_e32 v221, v88, v176
	v_sub_f32_e32 v223, v89, v176
	v_max3_f32 v66, v66, v67, v68
	v_max_f32_e32 v67, v220, v221
	v_max_f32_e32 v68, v222, v223
	v_sub_f32_e32 v90, v90, v176
	v_sub_f32_e32 v227, v91, v176
	v_max3_f32 v66, v66, v67, v68
	v_max_f32_e32 v67, v224, v90
	v_max_f32_e32 v68, v225, v227
	v_sub_f32_e32 v229, v92, v176
	v_sub_f32_e32 v231, v93, v176
	v_max3_f32 v66, v66, v67, v68
	v_max_f32_e32 v67, v228, v229
	v_max_f32_e32 v68, v230, v231
	v_sub_f32_e32 v233, v94, v176
	v_sub_f32_e32 v235, v95, v176
	v_max3_f32 v66, v66, v67, v68
	v_max_f32_e32 v67, v232, v233
	v_max_f32_e32 v68, v234, v235
	v_max3_f32 v66, v66, v67, v68
	v_mov_b32_e32 v67, v66
	s_nop 1
	v_permlane32_swap_b32_e32 v66, v67
	v_max3_f32 v226, v66, v67, 0
	v_sub_f32_e32 v64, v64, v226
	v_exp_f32_e32 v66, v64
	v_sub_f32_e32 v64, v80, v226
	v_sub_f32_e32 v65, v65, v226
	v_exp_f32_e32 v64, v64
	v_exp_f32_e32 v67, v65
	v_sub_f32_e32 v65, v81, v226
	v_sub_f32_e32 v68, v177, v226
	v_exp_f32_e32 v65, v65
	v_exp_f32_e32 v72, v68
	v_sub_f32_e32 v68, v82, v226
	v_exp_f32_e32 v68, v68
	v_add_f32_e32 v69, v66, v64
	v_add_f32_e32 v69, 0, v69
	v_add_f32_e32 v73, v67, v65
	v_pk_add_f32 v[70:71], v[72:73], v[68:69]
	v_sub_f32_e32 v69, v215, v226
	v_exp_f32_e32 v217, v69
	v_sub_f32_e32 v69, v83, v226
	v_exp_f32_e32 v81, v69
	v_sub_f32_e32 v69, v175, v226
	v_pk_add_f32 v[70:71], v[70:71], v[70:71] op_sel_hi:[0,1]
	v_exp_f32_e32 v88, v69
	v_sub_f32_e32 v69, v84, v226
	v_exp_f32_e32 v70, v69
	v_add_f32_e32 v89, v217, v81
	v_sub_f32_e32 v69, v216, v226
	v_exp_f32_e32 v73, v69
	v_pk_add_f32 v[74:75], v[88:89], v[70:71]
	v_sub_f32_e32 v69, v85, v226
	v_sub_f32_e32 v71, v218, v226
	v_pk_add_f32 v[76:77], v[74:75], v[74:75] op_sel_hi:[0,1]
	v_exp_f32_e32 v69, v69
	v_exp_f32_e32 v94, v71
	v_sub_f32_e32 v71, v86, v226
	v_exp_f32_e32 v76, v71
	v_sub_f32_e32 v71, v219, v226
	v_add_f32_e32 v95, v73, v69
	v_exp_f32_e32 v219, v71
	v_sub_f32_e32 v71, v87, v226
	v_pk_add_f32 v[74:75], v[94:95], v[76:77]
	v_exp_f32_e32 v83, v71
	v_sub_f32_e32 v71, v220, v226
	v_pk_add_f32 v[74:75], v[74:75], v[74:75] op_sel_hi:[0,1]
	v_exp_f32_e32 v92, v71
	v_sub_f32_e32 v71, v221, v226
	v_exp_f32_e32 v74, v71
	v_add_f32_e32 v93, v219, v83
	v_sub_f32_e32 v71, v222, v226
	v_sub_f32_e32 v77, v224, v226
	v_pk_add_f32 v[78:79], v[92:93], v[74:75]
	v_exp_f32_e32 v75, v71
	v_sub_f32_e32 v71, v223, v226
	v_pk_add_f32 v[78:79], v[78:79], v[78:79] op_sel_hi:[0,1]
	v_exp_f32_e32 v71, v71
	v_exp_f32_e32 v86, v77
	v_sub_f32_e32 v77, v90, v226
	v_exp_f32_e32 v78, v77
	v_add_f32_e32 v87, v75, v71
	v_sub_f32_e32 v77, v225, v226
	v_sub_f32_e32 v80, v232, v226
	v_pk_add_f32 v[84:85], v[86:87], v[78:79]
	v_exp_f32_e32 v87, v77
	v_sub_f32_e32 v77, v227, v226
	v_pk_add_f32 v[90:91], v[84:85], v[84:85] op_sel_hi:[0,1]
	v_exp_f32_e32 v85, v77
	v_sub_f32_e32 v77, v228, v226
	v_exp_f32_e32 v222, v77
	v_sub_f32_e32 v77, v229, v226
	v_exp_f32_e32 v90, v77
	v_add_f32_e32 v223, v87, v85
	v_sub_f32_e32 v77, v230, v226
	v_exp_f32_e32 v79, v77
	v_pk_add_f32 v[220:221], v[222:223], v[90:91]
	v_sub_f32_e32 v77, v231, v226
	v_pk_add_f32 v[220:221], v[220:221], v[220:221] op_sel_hi:[0,1]
	v_exp_f32_e32 v224, v80
	v_sub_f32_e32 v80, v233, v226
	v_exp_f32_e32 v77, v77
	v_exp_f32_e32 v220, v80
	v_sub_f32_e32 v80, v234, v226
	v_sub_f32_e32 v82, v235, v226
	v_add_f32_e32 v225, v79, v77
	v_pk_add_f32 v[228:229], v[224:225], v[220:221]
	v_exp_f32_e32 v91, v80
	v_exp_f32_e32 v221, v82
	v_exp_f32_e64 v80, -v226
	v_pk_add_f32 v[228:229], v[228:229], v[228:229] op_sel_hi:[0,1]
	v_mov_b32_e32 v227, v229
	v_add_f32_e32 v177, v91, v221
	v_pk_add_f32 v[176:177], v[176:177], v[226:227]
	v_mul_f32_e32 v241, v241, v80
	v_pk_mul_f32 v[62:63], v[62:63], v[80:81] op_sel_hi:[1,0]
	v_pk_mul_f32 v[60:61], v[60:61], v[80:81] op_sel_hi:[1,0]
	v_pk_mul_f32 v[58:59], v[58:59], v[80:81] op_sel_hi:[1,0]
	v_pk_mul_f32 v[56:57], v[56:57], v[80:81] op_sel_hi:[1,0]
	v_pk_mul_f32 v[54:55], v[54:55], v[80:81] op_sel_hi:[1,0]
	v_pk_mul_f32 v[52:53], v[52:53], v[80:81] op_sel_hi:[1,0]
	v_pk_mul_f32 v[50:51], v[50:51], v[80:81] op_sel_hi:[1,0]
	v_pk_mul_f32 v[48:49], v[48:49], v[80:81] op_sel_hi:[1,0]
	v_pk_mul_f32 v[30:31], v[30:31], v[80:81] op_sel_hi:[1,0]
	v_pk_mul_f32 v[28:29], v[28:29], v[80:81] op_sel_hi:[1,0]
	v_pk_mul_f32 v[26:27], v[26:27], v[80:81] op_sel_hi:[1,0]
	v_pk_mul_f32 v[24:25], v[24:25], v[80:81] op_sel_hi:[1,0]
	v_pk_mul_f32 v[22:23], v[22:23], v[80:81] op_sel_hi:[1,0]
	v_pk_mul_f32 v[20:21], v[20:21], v[80:81] op_sel_hi:[1,0]
	v_pk_mul_f32 v[18:19], v[18:19], v[80:81] op_sel_hi:[1,0]
	v_pk_mul_f32 v[16:17], v[16:17], v[80:81] op_sel_hi:[1,0]
	v_mov_b32_e32 v226, v177
	v_mov_b32_e32 v235, v220
	v_mov_b32_e32 v220, v77
	v_mov_b32_e32 v234, v90
	v_mov_b32_e32 v233, v78
	v_mov_b32_e32 v84, v71
	v_mov_b32_e32 v232, v74
	v_mov_b32_e32 v231, v76
	v_mov_b32_e32 v82, v69
	v_mov_b32_e32 v230, v70
	v_mov_b32_e32 v229, v68
	v_mov_b32_e32 v80, v65
	v_mov_b32_e32 v228, v64
	v_mov_b32_e32 v71, v224
	v_mov_b32_e32 v90, v79
	v_mov_b32_e32 v70, v222
	v_mov_b32_e32 v69, v86
	v_mov_b32_e32 v86, v75
	v_mov_b32_e32 v68, v92
	v_mov_b32_e32 v65, v94
	v_mov_b32_e32 v218, v73
	v_mov_b32_e32 v64, v88
	v_mov_b32_e32 v223, v72
	v_mov_b32_e32 v216, v67
	v_mov_b32_e32 v222, v66
	s_branch .LBB0_585

.LBB0_647:
	s_add_i32 s12, s7, 2
	s_cmp_ge_u32 s12, s19
	s_cbranch_scc1 .Lgq_nodma
	s_and_b32 s12, s12, 3
	s_mulk_i32 s12, 0x5000
	s_add_i32 s12, s5, s12
	s_mov_b32 m0, s12
	s_nop 0
	global_load_lds_dwordx4 v[148:149], off
	s_add_i32 m0, s12, 0x3000
	s_nop 0
	global_load_lds_dwordx4 v[150:151], off

.LBB0_649:
	s_add_i32 s10, s7, -1
	s_and_b32 s10, s10, 3
	s_mulk_i32 s10, 0x5000
	s_and_b32 s11, s7, 3
	v_add3_u32 v80, s10, v178, v177
	s_mulk_i32 s11, 0x5000
	v_add3_u32 v80, v80, v160, s51
	v_add_u32_e32 v81, s11, v175
	ds_read_b64_tr_b16 v[112:113], v80 offset:0
	ds_read_b64_tr_b16 v[114:115], v80 offset:1024
	ds_read_b64_tr_b16 v[140:141], v80 offset:512
	ds_read_b64_tr_b16 v[142:143], v80 offset:1536
	ds_read_b64_tr_b16 v[116:117], v80 offset:2048
	ds_read_b64_tr_b16 v[118:119], v80 offset:3072
	ds_read_b64_tr_b16 v[136:137], v80 offset:2560
	ds_read_b64_tr_b16 v[138:139], v80 offset:3584
	ds_read_b64_tr_b16 v[124:125], v80 offset:4096
	ds_read_b64_tr_b16 v[126:127], v80 offset:5120
	ds_read_b64_tr_b16 v[132:133], v80 offset:4608
	ds_read_b64_tr_b16 v[134:135], v80 offset:5632
	ds_read_b64_tr_b16 v[120:121], v80 offset:6144
	ds_read_b64_tr_b16 v[122:123], v80 offset:7168
	ds_read_b64_tr_b16 v[128:129], v80 offset:6656
	ds_read_b64_tr_b16 v[130:131], v80 offset:7680
	v_add_u32_e32 v80, v81, v165
	ds_read_b128 v[108:111], v80
	ds_read_b128 v[104:107], v80 offset:4096
	v_add_u32_e32 v80, v81, v172
	ds_read_b128 v[100:103], v80
	ds_read_b128 v[96:99], v80 offset:4096
	v_add_u32_e32 v80, v81, v168
	ds_read_b128 v[92:95], v80
	ds_read_b128 v[88:91], v80 offset:4096
	v_add_u32_e32 v80, v81, v167
	ds_read_b128 v[84:87], v80
	ds_read_b128 v[80:83], v80 offset:4096
	v_exp_f32_e32 v152, v48
	v_exp_f32_e32 v32, v32
	v_exp_f32_e32 v48, v33
	v_exp_f32_e32 v153, v50
	v_exp_f32_e32 v33, v34
	v_exp_f32_e32 v154, v49
	v_exp_f32_e32 v155, v51
	v_exp_f32_e32 v49, v35
	v_exp_f32_e32 v156, v52
	v_exp_f32_e32 v34, v36
	v_exp_f32_e32 v157, v54
	v_exp_f32_e32 v35, v38
	v_exp_f32_e32 v158, v53
	v_exp_f32_e32 v36, v37
	v_exp_f32_e32 v159, v55
	v_exp_f32_e32 v37, v39
	v_exp_f32_e32 v50, v56
	v_exp_f32_e32 v38, v40
	v_exp_f32_e32 v51, v58
	v_exp_f32_e32 v39, v42
	v_exp_f32_e32 v52, v57
	v_exp_f32_e32 v40, v41
	v_exp_f32_e32 v53, v59
	v_exp_f32_e32 v41, v43
	v_exp_f32_e32 v42, v44
	v_exp_f32_e32 v44, v45
	v_exp_f32_e32 v43, v46
	v_exp_f32_e32 v45, v47
	v_exp_f32_e32 v54, v60
	v_exp_f32_e32 v56, v61
	v_exp_f32_e32 v55, v62
	v_exp_f32_e32 v57, v63
	v_pk_add_f32 v[46:47], v[152:153], v[32:33]
	v_pk_add_f32 v[58:59], v[154:155], v[48:49]
	v_pk_add_f32 v[60:61], v[156:157], v[34:35]
	v_pk_add_f32 v[62:63], v[158:159], v[36:37]
	v_pk_add_f32 v[46:47], v[60:61], v[46:47]
	v_pk_add_f32 v[58:59], v[62:63], v[58:59]
	v_pk_add_f32 v[60:61], v[50:51], v[38:39]
	v_pk_add_f32 v[62:63], v[52:53], v[40:41]
	v_pk_add_f32 v[46:47], v[60:61], v[46:47]
	v_pk_add_f32 v[58:59], v[62:63], v[58:59]
	v_pk_add_f32 v[60:61], v[54:55], v[42:43]
	v_pk_add_f32 v[62:63], v[56:57], v[44:45]
	v_pk_add_f32 v[46:47], v[60:61], v[46:47]
	v_pk_add_f32 v[58:59], v[62:63], v[58:59]
	s_nop 0
	v_pk_add_f32 v[46:47], v[46:47], v[58:59]
	s_nop 0
	v_add_f32_e32 v146, v46, v47
	v_cmp_ngt_f32_e32 vcc, s92, v146
	s_cbranch_vccnz .Lgq_slow
.LBB0_651:
.LBB0_652:
	s_add_i32 s12, s7, 2
	s_cmp_ge_u32 s12, s19
	s_cselect_b64 s[10:11], -1, 0

.Lml_slow:
	v_add_u32_e32 v154, s14, v183
	v_add_u32_e32 v48, v154, v169
	ds_read_b128 v[32:35], v48
	v_add_u32_e32 v178, v154, v167
	ds_read_b128 v[174:177], v178
	ds_read_b128 v[48:51], v48 offset:4096
	s_mov_b64 s[12:13], -1
	s_waitcnt lgkmcnt(0)
	v_mfma_f32_32x32x16_bf16 v[32:47], v[32:35], v[84:87], 0
	v_mfma_f32_32x32x16_bf16 v[32:47], v[174:177], v[80:83], v[32:47]
	ds_read_b128 v[174:177], v178 offset:4096
	v_add_u32_e32 v178, v154, v165
	v_add_u32_e32 v154, v154, v163
	v_mfma_f32_32x32x16_bf16 v[48:63], v[48:51], v[84:87], 0
	s_waitcnt lgkmcnt(0)
	v_mfma_f32_32x32x16_bf16 v[48:63], v[174:177], v[80:83], v[48:63]
	ds_read_b128 v[174:177], v178
	s_waitcnt lgkmcnt(0)
	v_mfma_f32_32x32x16_bf16 v[32:47], v[174:177], v[76:79], v[32:47]
	ds_read_b128 v[174:177], v178 offset:4096
	s_waitcnt lgkmcnt(0)
	v_mfma_f32_32x32x16_bf16 v[48:63], v[174:177], v[76:79], v[48:63]
	ds_read_b128 v[174:177], v154
	s_waitcnt lgkmcnt(0)
	v_mfma_f32_32x32x16_bf16 v[32:47], v[174:177], v[72:75], v[32:47]
	ds_read_b128 v[174:177], v154 offset:4096
	s_waitcnt lgkmcnt(0)
	v_mfma_f32_32x32x16_bf16 v[48:63], v[174:177], v[72:75], v[48:63]
	ds_read_b128 v[174:177], v193 offset:8192
	s_waitcnt lgkmcnt(0)
	v_mfma_f32_32x32x16_bf16 v[32:47], v[174:177], v[68:71], v[32:47]
	ds_read_b128 v[174:177], v193 offset:10240
	s_waitcnt lgkmcnt(0)
	v_mfma_f32_32x32x16_bf16 v[48:63], v[174:177], v[68:71], v[48:63]
	ds_read_b128 v[174:177], v192 offset:8192
	s_waitcnt lgkmcnt(0)
	v_mfma_f32_32x32x16_bf16 v[32:47], v[174:177], v[64:67], v[32:47]
	ds_read_b128 v[174:177], v192 offset:10240
	s_waitcnt lgkmcnt(0)
	v_mfma_f32_32x32x16_bf16 v[48:63], v[174:177], v[64:67], v[48:63]
	s_nop 8
	v_sub_f32_e32 v32, v32, v155
	v_sub_f32_e32 v33, v33, v155
	v_sub_f32_e32 v34, v34, v155
	v_sub_f32_e32 v175, v35, v155
	v_sub_f32_e32 v36, v36, v155
	v_sub_f32_e32 v180, v37, v155
	v_sub_f32_e32 v38, v38, v155
	v_sub_f32_e32 v48, v48, v155
	v_sub_f32_e32 v49, v49, v155
	v_max_f32_e32 v154, v32, v48
	v_max_f32_e32 v174, v33, v49
	v_sub_f32_e32 v50, v50, v155
	v_sub_f32_e32 v51, v51, v155
	v_max3_f32 v154, v154, s93, v174
	v_max_f32_e32 v174, v34, v50
	v_max_f32_e32 v35, v175, v51
	v_sub_f32_e32 v52, v52, v155
	v_sub_f32_e32 v53, v53, v155
	v_max3_f32 v35, v154, v174, v35
	v_max_f32_e32 v154, v36, v52
	v_max_f32_e32 v37, v180, v53
	v_max3_f32 v35, v35, v154, v37
	v_sub_f32_e32 v54, v54, v155
	v_sub_f32_e32 v154, v39, v155
	v_sub_f32_e32 v55, v55, v155
	v_max_f32_e32 v37, v38, v54
	v_max_f32_e32 v39, v154, v55
	v_sub_f32_e32 v40, v40, v155
	v_sub_f32_e32 v56, v56, v155
	v_sub_f32_e32 v196, v41, v155
	v_sub_f32_e32 v57, v57, v155
	v_max3_f32 v35, v35, v37, v39
	v_max_f32_e32 v37, v40, v56
	v_max_f32_e32 v39, v196, v57
	v_sub_f32_e32 v42, v42, v155
	v_sub_f32_e32 v198, v58, v155
	v_sub_f32_e32 v199, v43, v155
	v_sub_f32_e32 v59, v59, v155
	v_max3_f32 v35, v35, v37, v39
	v_max_f32_e32 v37, v42, v198
	v_max_f32_e32 v39, v199, v59
	v_sub_f32_e32 v44, v44, v155
	v_sub_f32_e32 v200, v60, v155
	v_sub_f32_e32 v201, v45, v155
	v_sub_f32_e32 v202, v61, v155
	v_max3_f32 v35, v35, v37, v39
	v_max_f32_e32 v37, v44, v200
	v_max_f32_e32 v39, v201, v202
	v_sub_f32_e32 v203, v46, v155
	v_sub_f32_e32 v204, v62, v155
	v_sub_f32_e32 v205, v47, v155
	v_sub_f32_e32 v206, v63, v155
	v_max3_f32 v35, v35, v37, v39
	v_max_f32_e32 v37, v203, v204
	v_max_f32_e32 v39, v205, v206
	v_max3_f32 v35, v35, v37, v39
	v_mov_b32_e32 v37, v35
	s_nop 1
	v_permlane32_swap_b32_e32 v35, v37
	v_max3_f32 v207, v35, v37, 0
	v_sub_f32_e32 v32, v32, v207
	v_sub_f32_e32 v33, v33, v207
	v_exp_f32_e32 v174, v32
	v_sub_f32_e32 v32, v48, v207
	v_exp_f32_e32 v176, v33
	v_sub_f32_e32 v33, v49, v207
	v_exp_f32_e32 v32, v32
	v_exp_f32_e32 v48, v33
	v_sub_f32_e32 v33, v34, v207
	v_exp_f32_e32 v60, v33
	v_sub_f32_e32 v33, v50, v207
	v_exp_f32_e32 v46, v33
	v_add_f32_e32 v35, v174, v32
	v_sub_f32_e32 v33, v175, v207
	v_add_f32_e32 v47, 0, v35
	v_add_f32_e32 v61, v176, v48
	v_exp_f32_e32 v177, v33
	v_sub_f32_e32 v33, v51, v207
	v_pk_add_f32 v[34:35], v[60:61], v[46:47]
	v_exp_f32_e32 v49, v33
	v_sub_f32_e32 v33, v36, v207
	v_pk_add_f32 v[34:35], v[34:35], v[34:35] op_sel_hi:[0,1]
	v_exp_f32_e32 v178, v33
	v_sub_f32_e32 v33, v52, v207
	v_exp_f32_e32 v34, v33
	v_add_f32_e32 v179, v177, v49
	v_sub_f32_e32 v33, v180, v207
	v_exp_f32_e32 v180, v33
	v_pk_add_f32 v[36:37], v[178:179], v[34:35]
	v_sub_f32_e32 v33, v53, v207
	v_pk_add_f32 v[62:63], v[36:37], v[36:37] op_sel_hi:[0,1]
	v_exp_f32_e32 v36, v33
	v_sub_f32_e32 v33, v38, v207
	v_exp_f32_e32 v192, v33
	v_sub_f32_e32 v33, v54, v207
	v_exp_f32_e32 v62, v33
	v_sub_f32_e32 v33, v154, v207
	v_add_f32_e32 v193, v180, v36
	v_exp_f32_e32 v181, v33
	v_sub_f32_e32 v33, v55, v207
	v_pk_add_f32 v[38:39], v[192:193], v[62:63]
	v_exp_f32_e32 v37, v33
	v_sub_f32_e32 v33, v40, v207
	v_pk_add_f32 v[38:39], v[38:39], v[38:39] op_sel_hi:[0,1]
	v_exp_f32_e32 v50, v33
	v_sub_f32_e32 v33, v56, v207
	v_exp_f32_e32 v38, v33
	v_add_f32_e32 v51, v181, v37
	v_sub_f32_e32 v33, v196, v207
	v_exp_f32_e32 v52, v33
	v_pk_add_f32 v[40:41], v[50:51], v[38:39]
	v_sub_f32_e32 v33, v57, v207
	v_pk_add_f32 v[194:195], v[40:41], v[40:41] op_sel_hi:[0,1]
	v_exp_f32_e32 v40, v33
	v_sub_f32_e32 v33, v42, v207
	v_exp_f32_e32 v196, v33
	v_sub_f32_e32 v33, v198, v207
	v_exp_f32_e32 v194, v33
	v_sub_f32_e32 v33, v199, v207
	v_add_f32_e32 v197, v52, v40
	v_exp_f32_e32 v53, v33
	v_sub_f32_e32 v33, v59, v207
	v_pk_add_f32 v[42:43], v[196:197], v[194:195]
	v_exp_f32_e32 v41, v33
	v_sub_f32_e32 v33, v44, v207
	v_pk_add_f32 v[42:43], v[42:43], v[42:43] op_sel_hi:[0,1]
	v_exp_f32_e32 v54, v33
	v_sub_f32_e32 v33, v200, v207
	v_exp_f32_e32 v42, v33
	v_add_f32_e32 v55, v53, v41
	v_sub_f32_e32 v33, v201, v207
	v_exp_f32_e32 v56, v33
	v_pk_add_f32 v[44:45], v[54:55], v[42:43]
	v_sub_f32_e32 v33, v202, v207
	v_pk_add_f32 v[198:199], v[44:45], v[44:45] op_sel_hi:[0,1]
	v_exp_f32_e32 v44, v33
	v_sub_f32_e32 v33, v203, v207
	v_exp_f32_e32 v200, v33
	v_sub_f32_e32 v33, v204, v207
	v_exp_f32_e32 v198, v33
	v_sub_f32_e32 v33, v205, v207
	v_exp_f32_e32 v57, v33
	v_sub_f32_e32 v33, v206, v207
	v_exp_f32_e32 v45, v33
	v_exp_f32_e64 v58, -v207
	v_add_f32_e32 v201, v56, v44
	v_pk_add_f32 v[202:203], v[200:201], v[198:199]
	v_add_f32_e32 v154, v57, v45
	v_pk_add_f32 v[202:203], v[202:203], v[202:203] op_sel:[0,1] op_sel_hi:[1,0]
	v_pk_mul_f32 v[14:15], v[14:15], v[58:59] op_sel_hi:[1,0]
	v_mov_b32_e32 v203, v207
	v_pk_mul_f32 v[12:13], v[12:13], v[58:59] op_sel_hi:[1,0]
	v_pk_mul_f32 v[10:11], v[10:11], v[58:59] op_sel_hi:[1,0]
	v_pk_mul_f32 v[8:9], v[8:9], v[58:59] op_sel_hi:[1,0]
	v_pk_mul_f32 v[6:7], v[6:7], v[58:59] op_sel_hi:[1,0]
	v_pk_mul_f32 v[4:5], v[4:5], v[58:59] op_sel_hi:[1,0]
	v_pk_mul_f32 v[2:3], v[2:3], v[58:59] op_sel_hi:[1,0]
	v_pk_mul_f32 v[0:1], v[0:1], v[58:59] op_sel_hi:[1,0]
	v_pk_mul_f32 v[30:31], v[30:31], v[58:59] op_sel_hi:[1,0]
	v_pk_mul_f32 v[28:29], v[28:29], v[58:59] op_sel_hi:[1,0]
	v_pk_mul_f32 v[26:27], v[26:27], v[58:59] op_sel_hi:[1,0]
	v_pk_mul_f32 v[24:25], v[24:25], v[58:59] op_sel_hi:[1,0]
	v_pk_mul_f32 v[22:23], v[22:23], v[58:59] op_sel_hi:[1,0]
	v_pk_mul_f32 v[20:21], v[20:21], v[58:59] op_sel_hi:[1,0]
	v_pk_mul_f32 v[18:19], v[18:19], v[58:59] op_sel_hi:[1,0]
	v_pk_mul_f32 v[16:17], v[16:17], v[58:59] op_sel_hi:[1,0]
	v_pk_add_f32 v[154:155], v[154:155], v[202:203]
	v_mul_f32_e32 v185, v185, v58
	v_mov_b32_e32 v175, v60
	v_mov_b32_e32 v179, v192
	v_mov_b32_e32 v51, v196
	v_mov_b32_e32 v55, v200
	v_mov_b32_e32 v33, v46
	v_mov_b32_e32 v35, v62
	v_mov_b32_e32 v39, v194
	v_mov_b32_e32 v43, v198
	s_cmp_ge_u32 s7, s19
	s_cselect_b64 s[14:15], -1, 0
	s_and_b64 vcc, exec, s[14:15]
	s_branch .LBB0_687
.LBB0_680:
	s_cmp_ge_u32 s7, s19
	s_cbranch_scc1 .Lml_nodma
	s_and_b32 s16, s7, 3
	s_mulk_i32 s16, 0x5000
	s_add_i32 s16, s5, s16
	s_mov_b32 m0, s16
	s_and_b64 vcc, exec, s[10:11]
	global_load_lds_dwordx4 v[172:173], off
	s_add_i32 m0, s16, 0x3000
	s_nop 0
	global_load_lds_dwordx4 v[156:157], off
	s_cbranch_vccnz .Lml_nodma
	s_add_i32 m0, s16, 0x2000
	s_nop 0
	global_load_lds_dwordx4 v[158:159], off
.Lml_nodma:
	s_waitcnt lgkmcnt(0)
	v_mfma_f32_32x32x16_bf16 v[32:47], v[116:119], v[84:87], 0
	s_add_i32 s14, s7, -3
	s_and_b32 s14, s14, 3
	s_mulk_i32 s14, 0x5000
	v_add_u32_e32 v116, s14, v186
	v_mfma_f32_32x32x16_bf16 v[32:47], v[112:115], v[80:83], v[32:47]
	v_mfma_f32_32x32x16_bf16 v[48:63], v[108:111], v[84:87], 0
	v_add_u32_e32 v193, v116, v190
	v_add_u32_e32 v192, v116, v191
	ds_read_b128 v[108:111], v193 offset:8192
	ds_read_b128 v[112:115], v193 offset:10240
	ds_read_b128 v[116:119], v192 offset:8192
	ds_read_b128 v[120:123], v192 offset:10240
	v_mfma_f32_32x32x16_bf16 v[48:63], v[104:107], v[80:83], v[48:63]
	v_mfma_f32_32x32x16_bf16 v[32:47], v[100:103], v[76:79], v[32:47]
	s_andn2_b64 vcc, exec, s[12:13]
	v_mfma_f32_32x32x16_bf16 v[48:63], v[96:99], v[76:79], v[48:63]
	v_mfma_f32_32x32x16_bf16 v[32:47], v[92:95], v[72:75], v[32:47]
	v_mfma_f32_32x32x16_bf16 v[48:63], v[88:91], v[72:75], v[48:63]
	s_waitcnt lgkmcnt(0)
	v_mfma_f32_32x32x16_bf16 v[32:47], v[108:111], v[68:71], v[32:47]
	v_mfma_f32_32x32x16_bf16 v[48:63], v[112:115], v[68:71], v[48:63]
	v_mfma_f32_32x32x16_bf16 v[32:47], v[116:119], v[64:67], v[32:47]
	v_mfma_f32_32x32x16_bf16 v[48:63], v[120:123], v[64:67], v[48:63]
	s_cbranch_vccz .Lml_anym
.LBB0_682:
	s_add_i32 s15, s7, -2
	s_and_b32 s15, s15, 3
	v_add3_u32 v88, s14, v187, v188
	s_mulk_i32 s15, 0x5000
	v_add3_u32 v88, v88, v160, s51
	v_add_u32_e32 v89, s15, v189
	ds_read_b64_tr_b16 v[120:121], v88 offset:0
	ds_read_b64_tr_b16 v[122:123], v88 offset:1024
	ds_read_b64_tr_b16 v[148:149], v88 offset:512
	ds_read_b64_tr_b16 v[150:151], v88 offset:1536
	ds_read_b64_tr_b16 v[124:125], v88 offset:2048
	ds_read_b64_tr_b16 v[126:127], v88 offset:3072
	ds_read_b64_tr_b16 v[144:145], v88 offset:2560
	ds_read_b64_tr_b16 v[146:147], v88 offset:3584
	ds_read_b64_tr_b16 v[132:133], v88 offset:4096
	ds_read_b64_tr_b16 v[134:135], v88 offset:5120
	ds_read_b64_tr_b16 v[140:141], v88 offset:4608
	ds_read_b64_tr_b16 v[142:143], v88 offset:5632
	ds_read_b64_tr_b16 v[128:129], v88 offset:6144
	ds_read_b64_tr_b16 v[130:131], v88 offset:7168
	ds_read_b64_tr_b16 v[136:137], v88 offset:6656
	ds_read_b64_tr_b16 v[138:139], v88 offset:7680
	v_add_u32_e32 v88, v89, v169
	ds_read_b128 v[116:119], v88
	ds_read_b128 v[108:111], v88 offset:4096
	v_add_u32_e32 v88, v89, v167
	ds_read_b128 v[112:115], v88
	ds_read_b128 v[104:107], v88 offset:4096
	v_add_u32_e32 v88, v89, v165
	ds_read_b128 v[100:103], v88
	ds_read_b128 v[96:99], v88 offset:4096
	v_add_u32_e32 v88, v89, v163
	ds_read_b128 v[92:95], v88
	ds_read_b128 v[88:91], v88 offset:4096
	v_exp_f32_e32 v174, v32
	v_exp_f32_e32 v32, v48
	v_exp_f32_e32 v176, v33
	v_exp_f32_e32 v175, v34
	v_exp_f32_e32 v33, v50
	v_exp_f32_e32 v48, v49
	v_exp_f32_e32 v177, v35
	v_exp_f32_e32 v49, v51
	v_exp_f32_e32 v178, v36
	v_exp_f32_e32 v34, v52
	v_exp_f32_e32 v179, v38
	v_exp_f32_e32 v35, v54
	v_exp_f32_e32 v180, v37
	v_exp_f32_e32 v36, v53
	v_exp_f32_e32 v181, v39
	v_exp_f32_e32 v37, v55
	v_exp_f32_e32 v50, v40
	v_exp_f32_e32 v38, v56
	v_exp_f32_e32 v51, v42
	v_exp_f32_e32 v39, v58
	v_exp_f32_e32 v52, v41
	v_exp_f32_e32 v40, v57
	v_exp_f32_e32 v53, v43
	v_exp_f32_e32 v41, v59
	v_exp_f32_e32 v55, v46
	v_exp_f32_e32 v57, v47
	v_exp_f32_e32 v54, v44
	v_exp_f32_e32 v42, v60
	v_exp_f32_e32 v44, v61
	v_exp_f32_e32 v43, v62
	v_exp_f32_e32 v56, v45
	v_exp_f32_e32 v45, v63
	v_pk_add_f32 v[46:47], v[174:175], v[32:33]
	v_pk_add_f32 v[58:59], v[176:177], v[48:49]
	v_pk_add_f32 v[60:61], v[178:179], v[34:35]
	v_pk_add_f32 v[62:63], v[180:181], v[36:37]
	v_pk_add_f32 v[46:47], v[60:61], v[46:47]
	v_pk_add_f32 v[58:59], v[62:63], v[58:59]
	v_pk_add_f32 v[60:61], v[50:51], v[38:39]
	v_pk_add_f32 v[62:63], v[52:53], v[40:41]
	v_pk_add_f32 v[46:47], v[60:61], v[46:47]
	v_pk_add_f32 v[58:59], v[62:63], v[58:59]
	v_pk_add_f32 v[60:61], v[54:55], v[42:43]
	v_pk_add_f32 v[62:63], v[56:57], v[44:45]
	v_pk_add_f32 v[46:47], v[60:61], v[46:47]
	v_pk_add_f32 v[58:59], v[62:63], v[58:59]
	s_nop 0
	v_pk_add_f32 v[46:47], v[46:47], v[58:59]
	s_nop 0
	v_add_f32_e32 v154, v46, v47
	v_cmp_ngt_f32_e32 vcc, s92, v154
	s_cbranch_vccnz .Lml_slow
.LBB0_684:
	s_cmp_ge_u32 s7, s19
	s_cselect_b64 s[14:15], -1, 0
